# GDN chunk process: per-thread LDS table offsets kept in three persistent VGPRs and the (tid&7)==0 mask built from existing SGPR masks; 8 VALU per chunk fewer (on top of the norm partial batching)
# baseline (speedup 1.0000x reference)
; #define LAS __attribute__((address_space(3)))
; __device__ __forceinline__ float hload(const f16_t* p) { return (float)(*p); }
; __device__ __forceinline__ int tidx() { int t = threadIdx.x; asm volatile("" : "+v"(t)); return t; }
; template <int MIX, bool SAMPLE>
; __device__ __forceinline__ void rec_load(Raw<MIX>& R, const f16_t* proj, int chunk, int sg, int head, int vcol0) {
;     const int tid = tidx(), s = tid >> 3, cgi = tid & 7;
;     const Slot sl = slot_of<SAMPLE>(chunk, s, sg);
;     const f16_t* rowp = proj + (size_t)sl.row * PN;
;     if constexpr (MIX == 0) {
;         R.hq = *(const u32x4*)(rowp + C_HQ + head * 64 + cgi * 8);
;         R.hf = *(const u32x4*)(rowp + C_HF + head * 64 + cgi * 8);
;         R.hi = *(const u32x2*)(rowp + C_HI + head * 64 + vcol0 + cgi * 4);
;     } else if constexpr (MIX == 1) {
;         R.q = *(const u32x4*)(rowp + C_GQKV + head * 64 + cgi * 8);
;         R.k = *(const u32x4*)(rowp + C_GQKV + 256 + head * 64 + cgi * 8);
;         R.v = *(const u32x2*)(rowp + C_GQKV + 512 + head * 64 + vcol0 + cgi * 4);
;         R.ga = hload(rowp + C_GA + head); R.gb = hload(rowp + C_GB + head);
;     ...
;     if constexpr (MIX == 1) {
;         constexpr int BUF = C::OFF_O + 2048;
;         rec_load<MIX, false>(R, proj, 0, sg, head, vcol0);
;         rec_process<MIX, false>(R, par, l, L, 0, sg, head);
;         __syncthreads();
;         rec_load<MIX, false>(R, proj, 1, sg, head, vcol0);
; #pragma unroll 1
;         for (int c = 0; c < SEQ / 64; ++c) {
;             LAS float* Lc = L + (c & 1) * BUF;
; #pragma unroll 1
;             for (int g = 0; g < (act ? 4 : 0); ++g) { float pp[16];
.LBB0_410:
	s_or_b64 exec, exec, s[4:5]
	v_mov_b32_e32 v0, v202
	s_waitcnt lgkmcnt(0)
	s_barrier
	s_lshl_b32 s2, s30, 6
	v_ashrrev_i32_e32 v1, 3, v0
	v_and_b32_e32 v2, 7, v0
	v_add3_u32 v3, v1, s10, 64
	v_mov_b64_e32 v[0:1], s[54:55]
	s_lshl_b32 s11, s34, 5
	v_mad_i64_i32 v[12:13], s[4:5], v3, s18, v[0:1]
	s_lshl_b32 s78, s2, 1
	s_mov_b32 s57, s79
	v_lshl_add_u64 v[8:9], v[12:13], 0, s[78:79]
	v_lshlrev_b32_e32 v0, 4, v2
	v_mov_b32_e32 v1, v17
	s_lshl_b32 s4, s11, 1
	s_mov_b32 s5, s79
	v_lshl_add_u64 v[12:13], v[12:13], 0, s[56:57]
	v_lshlrev_b32_e32 v16, 3, v2
	s_waitcnt vmcnt(0)
	v_lshl_add_u64 v[4:5], v[8:9], 0, v[0:1]
	v_lshl_add_u64 v[8:9], v[8:9], 0, s[4:5]
	v_add_co_u32_e32 v12, vcc, s20, v12
	v_lshl_add_u64 v[8:9], v[8:9], 0, v[16:17]
	s_nop 0
	v_addc_co_u32_e32 v13, vcc, 0, v13, vcc
	v_add_co_u32_e32 v176, vcc, 0x88000, v4
	s_nop 1
	v_addc_co_u32_e32 v177, vcc, 0, v5, vcc
	v_add_co_u32_e32 v178, vcc, 0x88000, v8
	s_nop 1
	v_addc_co_u32_e32 v179, vcc, 0, v9, vcc
	v_add_co_u32_e32 v180, vcc, 0x88000, v12
	s_nop 1
	v_addc_co_u32_e32 v181, vcc, 0, v13, vcc
	global_load_dwordx4 v[0:3], v[4:5], off offset:2048
	s_nop 0
	global_load_dwordx4 v[4:7], v[4:5], off offset:2560
	v_bfe_u32 v21, v10, 4, 2
	global_load_dwordx2 v[8:9], v[8:9], off offset:3072
	v_ashrrev_i32_e32 v11, 4, v10
	global_load_ushort v23, v[12:13], off
	v_and_b32_e32 v20, 15, v10
	global_load_ushort v24, v[12:13], off offset:8
	v_and_b32_e32 v13, 2, v10
	v_and_b32_e32 v22, -4, v11
	s_add_i32 s2, 0, 0x8000
	v_cmp_gt_i32_e64 s[42:43], 32, v22
	s_mov_b32 s12, 0
	v_cmp_gt_u32_e64 s[44:45], 8, v20
	v_cmp_eq_u32_e64 s[48:49], 0, v13
	s_or_b32 s13, s10, 0x80
	v_lshl_add_u32 v26, v20, 4, 0
	v_and_b32_e32 v12, 4, v10
	v_and_b32_e32 v10, 1, v10
	v_cmp_eq_u32_e64 s[50:51], 0, v10
	v_lshlrev_b32_e32 v10, 2, v11
	v_lshlrev_b32_e32 v11, 2, v21
	v_and_or_b32 v10, v10, -16, v11
	v_add_u32_e32 v25, s2, v10
	v_lshlrev_b32_e32 v11, 7, v20
	s_add_i32 s2, 0, 0xc400
	v_add3_u32 v27, v10, v11, s2
	v_mov_b32_e32 v10, 0
	v_cmp_eq_u32_e64 s[46:47], 0, v12
	v_mov_b32_e32 v11, v10
	v_mov_b32_e32 v12, v10
	v_mov_b32_e32 v13, v10
	v_ashrrev_i32_e32 v187, 3, v202
	v_lshlrev_b32_e32 v186, 2, v202
	v_and_b32_e32 v186, 28, v186
	v_lshlrev_b32_e32 v182, 7, v187
	v_lshl_add_u32 v182, v186, 2, v182
	v_and_b32_e32 v194, 7, v202
	v_lshlrev_b32_e32 v192, 8, v187
	v_lshl_add_u32 v192, v194, 5, v192
	v_lshlrev_b32_e32 v193, 7, v187
	v_lshl_add_u32 v193, v194, 4, v193
	v_lshlrev_b32_e32 v194, 4, v187
	v_add_u32_e32 v184, s10, v187
	v_ashrrev_i32_e32 v185, 31, v184
	v_lshlrev_b64 v[184:185], 11, v[184:185]
	v_lshl_add_u64 v[184:185], s[52:53], 0, v[184:185]
	v_lshl_add_u64 v[184:185], v[184:185], 0, s[78:79]
	v_lshl_add_u64 v[184:185], v[184:185], 0, s[4:5]
	v_lshlrev_b32_e32 v186, 1, v186
	v_mov_b32_e32 v187, 0
	v_lshl_add_u64 v[184:185], v[184:185], 0, v[186:187]
	v_add_co_u32_e32 v184, vcc, 0x3500000, v184
	s_nop 1
	v_addc_co_u32_e32 v185, vcc, 0, v185, vcc
	s_bitcmp1_b32 s12, 0
	s_cselect_b32 s22, 0x3900, 0
	s_and_saveexec_b64 s[6:7], s[42:43]
	s_cbranch_execz .LBB0_413

; #define LAS __attribute__((address_space(3)))
; __device__ __forceinline__ float sigmoidf_(float x) { return 1.0f / (1.0f + __expf(-x)); }
; __device__ __forceinline__ float softplusf_(float x) { return x > 20.f ? x : log1pf(expf(x)); }
; __device__ __forceinline__ float red8(float x) { x = red4(x); x += dppf<0x141>(x); return x; }
; __device__ __forceinline__ void u4f(const u32x4& u, float (&f)[8]) { h2f(u.x, f[0], f[1]); h2f(u.y, f[2], f[3]); h2f(u.z, f[4], f[5]); h2f(u.w, f[6], f[7]); }
; __device__ __forceinline__ void u2f(const u32x2& u, float (&f)[4]) { h2f(u.x, f[0], f[1]); h2f(u.y, f[2], f[3]); }
; template <int MIX, bool SAMPLE>
; __device__ __forceinline__ void rec_process(const Raw<MIX>& R, const MixPar& par, int l, LAS float* L, int chunk, int sg, int head) {
;     ...
;     } else if constexpr (MIX == 1) {
;         float q[8], k[8], v[4]; u4f(R.q, q); u4f(R.k, k); u2f(R.v, v);
;         float sq = 0.f, sk = 0.f;
; #pragma unroll
;         for (int i = 0; i < 8; ++i) { sq += q[i] * q[i]; sk += k[i] * k[i]; }
;         sq = red8(sq); sk = red8(sk);
;         const float rq = rsqrtf(sq + EPS) * 0.125f, rk = rsqrtf(sk + EPS);
;         float kq = 0.f;
; #pragma unroll
;         for (int i = 0; i < 8; ++i) { q[i] *= rq; k[i] *= rk; kq += q[i] * k[i]; }
;         kq = red8(kq);
;         *(LAS f32x4*)(L + C::OFF_Q + s * 64 + cgi * 8) = (f32x4){q[0], q[1], q[2], q[3]}; *(LAS f32x4*)(L + C::OFF_Q + s * 64 + cgi * 8 + 4) = (f32x4){q[4], q[5], q[6], q[7]};
;         *(LAS f32x4*)(L + C::OFF_K + s * 64 + cgi * 8) = (f32x4){k[0], k[1], k[2], k[3]}; *(LAS f32x4*)(L + C::OFF_K + s * 64 + cgi * 8 + 4) = (f32x4){k[4], k[5], k[6], k[7]};
;         *(LAS f32x4*)(L + C::OFF_V + s * 32 + cgi * 4) = (f32x4){v[0], v[1], v[2], v[3]};
;         if (cgi == 0) { const float a = expf(-par.f[0] * softplusf_(R.ga + par.f[1]));
;             *(LAS f32x4*)(L + C::OFF_SC + s * 4) = (f32x4){a, sigmoidf_(R.gb), kq, 0.f}; }
.LBB0_413:
	s_or_b64 exec, exec, s[6:7]
	s_add_i32 s2, s12, 1
	s_cmp_lg_u32 s12, 31
	s_cbranch_scc0 .LBB0_420
	s_waitcnt vmcnt(0)
	v_cvt_f32_f16_e32 v23, v23
	v_cvt_f32_f16_e32 v24, v24
	v_cvt_f32_f16_sdwa v31, v0 dst_sel:DWORD dst_unused:UNUSED_PAD src0_sel:WORD_1
	v_cvt_f32_f16_e32 v30, v0
	s_waitcnt vmcnt(1)
	v_cvt_f32_f16_sdwa v47, v4 dst_sel:DWORD dst_unused:UNUSED_PAD src0_sel:WORD_1
	v_cvt_f32_f16_e32 v46, v4
	v_cvt_f32_f16_sdwa v41, v1 dst_sel:DWORD dst_unused:UNUSED_PAD src0_sel:WORD_1
	v_cvt_f32_f16_e32 v40, v1
	v_cvt_f32_f16_sdwa v49, v5 dst_sel:DWORD dst_unused:UNUSED_PAD src0_sel:WORD_1
	v_cvt_f32_f16_e32 v48, v5
	v_cvt_f32_f16_sdwa v15, v2 dst_sel:DWORD dst_unused:UNUSED_PAD src0_sel:WORD_1
	v_cvt_f32_f16_e32 v14, v2
	v_cvt_f32_f16_sdwa v43, v6 dst_sel:DWORD dst_unused:UNUSED_PAD src0_sel:WORD_1
	v_cvt_f32_f16_e32 v42, v6
	v_pk_mul_f32 v[38:39], v[30:31], v[30:31]
	v_pk_mul_f32 v[54:55], v[46:47], v[46:47]
	v_cvt_f32_f16_sdwa v37, v3 dst_sel:DWORD dst_unused:UNUSED_PAD src0_sel:WORD_1
	v_cvt_f32_f16_e32 v36, v3
	v_cvt_f32_f16_sdwa v45, v7 dst_sel:DWORD dst_unused:UNUSED_PAD src0_sel:WORD_1
	v_cvt_f32_f16_e32 v44, v7
	v_pk_fma_f32 v[38:39], v[40:41], v[40:41], v[38:39]
	v_pk_fma_f32 v[54:55], v[48:49], v[48:49], v[54:55]
	v_pk_fma_f32 v[38:39], v[14:15], v[14:15], v[38:39]
	v_pk_fma_f32 v[54:55], v[42:43], v[42:43], v[54:55]
	v_pk_fma_f32 v[38:39], v[36:37], v[36:37], v[38:39]
	v_pk_fma_f32 v[54:55], v[44:45], v[44:45], v[54:55]
	v_add_f32_e32 v29, v38, v39
	v_add_f32_e32 v28, v54, v55
	s_bitcmp1_b32 s2, 0
	s_cselect_b32 s3, 0xe400, 0
	v_mov_b32_dpp v33, v29 quad_perm:[1,0,3,2] row_mask:0xf bank_mask:0xf bound_ctrl:1
	v_mov_b32_dpp v32, v28 quad_perm:[1,0,3,2] row_mask:0xf bank_mask:0xf bound_ctrl:1
	v_pk_add_f32 v[28:29], v[28:29], v[32:33]
	s_add_i32 s3, s3, 0
	s_nop 0
	v_mov_b32_dpp v33, v29 quad_perm:[2,3,0,1] row_mask:0xf bank_mask:0xf bound_ctrl:1
	v_mov_b32_dpp v32, v28 quad_perm:[2,3,0,1] row_mask:0xf bank_mask:0xf bound_ctrl:1
	v_pk_add_f32 v[28:29], v[28:29], v[32:33]
	s_nop 1
	v_mov_b32_dpp v33, v29 row_half_mirror row_mask:0xf bank_mask:0xf bound_ctrl:1
	v_mov_b32_dpp v32, v28 row_half_mirror row_mask:0xf bank_mask:0xf bound_ctrl:1
	v_pk_add_f32 v[28:29], v[28:29], v[32:33]
	s_nop 0
	v_pk_add_f32 v[32:33], v[28:29], s[66:67] op_sel_hi:[1,0]
	s_nop 0
	v_rsq_f32_e32 v16, v33
	v_rsq_f32_e32 v38, v32
	v_mul_f32_e32 v16, 0x3e000000, v16
	v_pk_mul_f32 v[34:35], v[16:17], v[14:15] op_sel_hi:[0,1]
	v_pk_mul_f32 v[30:31], v[16:17], v[30:31] op_sel_hi:[0,1]
	v_pk_mul_f32 v[32:33], v[16:17], v[40:41] op_sel_hi:[0,1]
	v_pk_mul_f32 v[36:37], v[16:17], v[36:37] op_sel_hi:[0,1]
	v_mov_b32_e32 v14, v38
	v_pk_mul_f32 v[38:39], v[14:15], v[46:47] op_sel_hi:[0,1]
	v_pk_mul_f32 v[40:41], v[14:15], v[48:49] op_sel_hi:[0,1]
	v_cvt_f32_f16_sdwa v49, v9 dst_sel:DWORD dst_unused:UNUSED_PAD src0_sel:WORD_1
	v_pk_mul_f32 v[42:43], v[14:15], v[42:43] op_sel_hi:[0,1]
	v_cvt_f32_f16_e32 v48, v9
	v_pk_mul_f32 v[44:45], v[14:15], v[44:45] op_sel_hi:[0,1]
	v_cvt_f32_f16_sdwa v47, v8 dst_sel:DWORD dst_unused:UNUSED_PAD src0_sel:WORD_1
	v_cvt_f32_f16_e32 v46, v8
	v_add_u32_e32 v29, s3, v192
	ds_write_b128 v29, v[30:33]
	ds_write_b128 v29, v[34:37] offset:16
	ds_write_b128 v29, v[38:41] offset:16384
	ds_write_b128 v29, v[42:45] offset:16400
	v_add_u32_e32 v29, s3, v193
	v_mul_f32_e32 v60, 0xbfb8aa3b, v24
	v_exp_f32_e32 v60, v60
	s_nop 0
	v_add_f32_e32 v60, 1.0, v60
	v_rcp_f32_e32 v60, v60
	s_nop 0
	v_pk_mul_f32 v[46:47], v[46:47], v[60:61] op_sel_hi:[1,0]
	v_pk_mul_f32 v[48:49], v[48:49], v[60:61] op_sel_hi:[1,0]
	ds_write_b128 v29, v[46:49] offset:32768
	s_and_b64 s[6:7], s[46:47], s[48:49]
	s_and_b64 s[6:7], s[6:7], s[50:51]
	s_and_saveexec_b64 s[6:7], s[6:7]
	s_cbranch_execz .LBB0_418
	v_add_f32_e32 v16, v18, v23
	v_cmp_nlt_f32_e32 vcc, s23, v16
	s_and_saveexec_b64 s[8:9], vcc
	s_cbranch_execz .LBB0_417
	v_mul_f32_e32 v29, 0x3fb8aa3b, v16
	v_rndne_f32_e32 v30, v29
	v_sub_f32_e32 v31, v29, v30
	v_fma_f32 v29, v16, s19, -v29
	v_fmac_f32_e32 v29, 0x32a5705f, v16
	v_add_f32_e32 v29, v31, v29
	v_cvt_i32_f32_e32 v30, v30
	v_exp_f32_e32 v29, v29
	v_cmp_ngt_f32_e32 vcc, s96, v16
	v_ldexp_f32 v29, v29, v30
	s_nop 0
	v_cndmask_b32_e32 v29, 0, v29, vcc
	v_cmp_nlt_f32_e32 vcc, s97, v16
	s_nop 1
	v_cndmask_b32_e32 v16, v216, v29, vcc
	v_add_f32_e32 v29, 1.0, v16
	v_add_f32_e32 v30, -1.0, v29
	v_log_f32_e32 v31, v29
	v_rcp_f32_e32 v29, v30
	v_cmp_eq_f32_e32 vcc, 0, v30
	v_mul_f32_e32 v31, 0x3f317218, v31
	v_mul_f32_e32 v29, v16, v29
	v_mul_f32_e32 v31, v31, v29
	v_cndmask_b32_e32 v16, v31, v16, vcc
.LBB0_417:
	s_or_b64 exec, exec, s[8:9]
	v_mul_f32_e32 v29, v19, v16
	v_mul_f32_e32 v16, 0x3fb8aa3b, v29
	v_fma_f32 v30, v29, s19, -v16
	v_rndne_f32_e32 v31, v16
	v_fmac_f32_e32 v30, 0x32a5705f, v29
	v_sub_f32_e32 v16, v16, v31
	v_add_f32_e32 v16, v16, v30
	v_exp_f32_e32 v30, v16
	v_cvt_i32_f32_e32 v31, v31
	v_cmp_ngt_f32_e32 vcc, s96, v29
	v_ldexp_f32 v14, v30, v31
	s_nop 0
	v_cndmask_b32_e32 v14, 0, v14, vcc
	v_cmp_nlt_f32_e32 vcc, s97, v29
	v_add_u32_e32 v28, s3, v194
	s_nop 0
	v_cndmask_b32_e32 v14, v216, v14, vcc
	v_mul_f32_e32 v15, v14, v60
	ds_write_b128 v28, v[14:17] offset:49152
